# nt cache policy on the 8 EpiAct (ACT) stores
# baseline (speedup 1.0000x reference)
; #define PG8_LAS __attribute__((address_space(3)))
; __device__ __forceinline__ unsigned cvt_pk_bf16(float lo, float hi) { unsigned r; asm volatile("v_cvt_pk_bf16_f32 %0, %1, %2" : "=v"(r) : "v"(lo), "v"(hi)); return r; }
; __device__ __forceinline__ float silu_mul(float g, float u) { return g * u * __builtin_amdgcn_rcpf(1.0f + __builtin_amdgcn_exp2f(-1.4426950408889634f * g)); }
;     __device__ __forceinline__ void operator()(const f32x4 (&acc)[2][2][4][2], const Unit& u, int wr, int wc, int fr, int fq) const {
;         const int row0 = u.pm * BM + wr * 64 + fr, col0 = u.pn * HALF + wc * 32 + 8 * fq;
;         float rsv[8]; { const PG8_LAS float* t_ = rt.rows(u.pm) + wr * 64 + fr;
; #pragma unroll
;             for (int it = 0; it < 8; ++it) rsv[it] = t_[(it >> 2) * HALF + (it & 3) * 16]; }
; #pragma unroll
;         for (int ai = 0; ai < 2; ++ai)
; #pragma unroll
;             for (int m = 0; m < 4; ++m) {
;                 const int row = row0 + ai * HALF + m * 16; const float rs = rsv[ai * 4 + m];
;                 const f32x4 g0 = acc[ai][0][m][0] * rs, g1 = acc[ai][0][m][1] * rs, u0 = acc[ai][1][m][0] * rs, u1 = acc[ai][1][m][1] * rs;
;                 u32x4e w;
;                 w.x = cvt_pk_bf16(silu_mul(g0[0], u0[0]), silu_mul(g0[1], u0[1])); w.y = cvt_pk_bf16(silu_mul(g0[2], u0[2]), silu_mul(g0[3], u0[3]));
;                 w.z = cvt_pk_bf16(silu_mul(g1[0], u1[0]), silu_mul(g1[1], u1[1])); w.w = cvt_pk_bf16(silu_mul(g1[2], u1[2]), silu_mul(g1[3], u1[3]));
;                 *(u32x4e*)(O + (size_t)row * ldo + col0) = w;
;             }
.LBB0_402:
	s_cmp_eq_u32 s35, s16
	s_cselect_b32 s9, 0x200, s23
	s_cmp_lg_u32 s35, s17
	s_cselect_b32 s9, s9, 0x100
	s_cmp_lg_u32 s35, s18
	s_cselect_b32 s9, s9, 0
	v_lshl_add_u32 v138, s9, 2, v150
	ds_read2_b32 v[144:145], v138 offset1:16
	ds_read2_b32 v[142:143], v138 offset0:32 offset1:48
	ds_read2_b32 v[140:141], v138 offset0:128 offset1:144
	ds_read2_b32 v[138:139], v138 offset0:160 offset1:176
	v_lshl_or_b32 v146, s34, 7, v151
	s_waitcnt lgkmcnt(0)
	v_pk_mul_f32 v[124:125], v[124:125], v[144:145] op_sel_hi:[1,0]
	v_pk_mul_f32 v[116:117], v[116:117], v[144:145] op_sel_hi:[1,0]
	v_pk_mul_f32 v[126:127], v[126:127], v[144:145] op_sel_hi:[1,0]
	v_mul_f32_e32 v116, v124, v116
	v_mul_f32_e32 v124, 0xbfb8aa3b, v124
	v_exp_f32_e32 v124, v124
	v_mul_f32_e32 v117, v125, v117
	v_pk_mul_f32 v[118:119], v[118:119], v[144:145] op_sel_hi:[1,0]
	v_pk_mul_f32 v[120:121], v[120:121], v[144:145] op_sel_hi:[1,0]
	v_add_f32_e32 v124, 1.0, v124
	v_rcp_f32_e32 v124, v124
	v_pk_mul_f32 v[112:113], v[112:113], v[144:145] op_sel_hi:[1,0]
	v_pk_mul_f32 v[122:123], v[122:123], v[144:145] op_sel_hi:[1,0]
	v_mul_f32_e32 v112, v120, v112
	v_mul_f32_e32 v116, v116, v124
	v_mul_f32_e32 v124, 0xbfb8aa3b, v125
	v_exp_f32_e32 v124, v124
	v_mul_f32_e32 v113, v121, v113
	v_pk_mul_f32 v[114:115], v[114:115], v[144:145] op_sel_hi:[1,0]
	v_lshl_add_u32 v153, s35, 8, v148
	v_add_f32_e32 v124, 1.0, v124
	v_rcp_f32_e32 v124, v124
	v_ashrrev_i32_e32 v147, 31, v146
	v_pk_mul_f32 v[92:93], v[92:93], v[142:143] op_sel_hi:[1,0]
	v_pk_mul_f32 v[84:85], v[84:85], v[142:143] op_sel_hi:[1,0]
	v_mul_f32_e32 v117, v117, v124
	v_cvt_pk_bf16_f32 v116, v116, v117
	v_mul_f32_e32 v117, v126, v118
	v_mul_f32_e32 v118, 0xbfb8aa3b, v126
	v_exp_f32_e32 v118, v118
	v_pk_mul_f32 v[94:95], v[94:95], v[142:143] op_sel_hi:[1,0]
	v_pk_mul_f32 v[86:87], v[86:87], v[142:143] op_sel_hi:[1,0]
	v_pk_mul_f32 v[88:89], v[88:89], v[142:143] op_sel_hi:[1,0]
	v_add_f32_e32 v118, 1.0, v118
	v_rcp_f32_e32 v118, v118
	v_pk_mul_f32 v[90:91], v[90:91], v[142:143] op_sel_hi:[1,0]
	v_pk_mul_f32 v[60:61], v[60:61], v[140:141] op_sel_hi:[1,0]
	v_pk_mul_f32 v[52:53], v[52:53], v[140:141] op_sel_hi:[1,0]
	v_mul_f32_e32 v117, v117, v118
	v_mul_f32_e32 v118, v127, v119
	v_mul_f32_e32 v119, 0xbfb8aa3b, v127
	v_exp_f32_e32 v119, v119
	v_pk_mul_f32 v[62:63], v[62:63], v[140:141] op_sel_hi:[1,0]
	v_pk_mul_f32 v[54:55], v[54:55], v[140:141] op_sel_hi:[1,0]
	v_pk_mul_f32 v[56:57], v[56:57], v[140:141] op_sel_hi:[1,0]
	v_add_f32_e32 v119, 1.0, v119
	v_rcp_f32_e32 v119, v119
	v_pk_mul_f32 v[58:59], v[58:59], v[140:141] op_sel_hi:[1,0]
	v_pk_mul_f32 v[28:29], v[28:29], v[138:139] op_sel_hi:[1,0]
	v_pk_mul_f32 v[20:21], v[20:21], v[138:139] op_sel_hi:[1,0]
	v_mul_f32_e32 v118, v118, v119
	v_cvt_pk_bf16_f32 v117, v117, v118
	v_mul_f32_e32 v118, 0xbfb8aa3b, v120
	v_exp_f32_e32 v118, v118
	v_pk_mul_f32 v[30:31], v[30:31], v[138:139] op_sel_hi:[1,0]
	v_pk_mul_f32 v[22:23], v[22:23], v[138:139] op_sel_hi:[1,0]
	v_pk_mul_f32 v[24:25], v[24:25], v[138:139] op_sel_hi:[1,0]
	v_add_f32_e32 v118, 1.0, v118
	v_rcp_f32_e32 v118, v118
	v_pk_mul_f32 v[26:27], v[26:27], v[138:139] op_sel_hi:[1,0]
	s_andn2_b64 vcc, exec, s[38:39]
	v_mul_f32_e32 v112, v112, v118
	v_mul_f32_e32 v118, 0xbfb8aa3b, v121
	v_exp_f32_e32 v118, v118
	s_nop 0
	v_add_f32_e32 v118, 1.0, v118
	v_rcp_f32_e32 v118, v118
	s_nop 0
	v_mul_f32_e32 v113, v113, v118
	v_cvt_pk_bf16_f32 v118, v112, v113
	v_mul_f32_e32 v113, 0xbfb8aa3b, v122
	v_mul_f32_e32 v112, v122, v114
	v_exp_f32_e32 v113, v113
	v_mul_f32_e32 v114, 0xbfb8aa3b, v123
	v_exp_f32_e32 v114, v114
	v_add_f32_e32 v113, 1.0, v113
	v_rcp_f32_e32 v113, v113
	v_add_f32_e32 v114, 1.0, v114
	v_rcp_f32_e32 v114, v114
	v_mul_f32_e32 v112, v112, v113
	v_mul_f32_e32 v113, v123, v115
	v_mul_f32_e32 v113, v113, v114
	v_cvt_pk_bf16_f32 v119, v112, v113
	v_mov_b64_e32 v[112:113], s[90:91]
	v_mad_i64_i32 v[120:121], s[10:11], v153, s24, v[112:113]
	v_lshlrev_b64 v[114:115], 1, v[146:147]
	v_lshl_add_u64 v[120:121], v[120:121], 0, v[114:115]
	global_store_dwordx4 v[120:121], v[116:119], off nt
	s_nop 1
	v_or_b32_e32 v117, 16, v153
	v_mov_b32_e32 v116, v145
	v_pk_mul_f32 v[108:109], v[108:109], v[116:117] op_sel_hi:[1,0]
	v_pk_mul_f32 v[100:101], v[100:101], v[116:117] op_sel_hi:[1,0]
	v_pk_mul_f32 v[118:119], v[98:99], v[116:117] op_sel_hi:[1,0]
	v_pk_mul_f32 v[98:99], v[96:97], v[116:117] op_sel_hi:[1,0]
	v_mul_f32_e32 v97, 0xbfb8aa3b, v108
	v_mul_f32_e32 v96, v108, v100
	v_exp_f32_e32 v97, v97
	v_mul_f32_e32 v100, 0xbfb8aa3b, v109
	v_exp_f32_e32 v100, v100
	v_pk_mul_f32 v[110:111], v[110:111], v[116:117] op_sel_hi:[1,0]
	v_add_f32_e32 v97, 1.0, v97
	v_rcp_f32_e32 v97, v97
	v_add_f32_e32 v100, 1.0, v100
	v_rcp_f32_e32 v100, v100
	v_pk_mul_f32 v[102:103], v[102:103], v[116:117] op_sel_hi:[1,0]
	v_mul_f32_e32 v96, v96, v97
	v_mul_f32_e32 v97, v109, v101
	v_mul_f32_e32 v97, v97, v100
	v_mul_f32_e32 v100, 0xbfb8aa3b, v110
	v_exp_f32_e32 v100, v100
	v_mul_f32_e32 v101, 0xbfb8aa3b, v111
	v_exp_f32_e32 v101, v101
	v_cvt_pk_bf16_f32 v96, v96, v97
	v_add_f32_e32 v100, 1.0, v100
	v_rcp_f32_e32 v100, v100
	v_add_f32_e32 v101, 1.0, v101
	v_rcp_f32_e32 v101, v101
	v_mul_f32_e32 v97, v110, v102
	v_mul_f32_e32 v97, v97, v100
	v_mul_f32_e32 v100, v111, v103
	v_pk_mul_f32 v[104:105], v[104:105], v[116:117] op_sel_hi:[1,0]
	v_mul_f32_e32 v100, v100, v101
	v_cvt_pk_bf16_f32 v97, v97, v100
	v_mul_f32_e32 v100, 0xbfb8aa3b, v104
	v_exp_f32_e32 v100, v100
	v_mul_f32_e32 v98, v104, v98
	v_pk_mul_f32 v[106:107], v[106:107], v[116:117] op_sel_hi:[1,0]
	v_mul_f32_e32 v99, v105, v99
	v_add_f32_e32 v100, 1.0, v100
	v_rcp_f32_e32 v100, v100
	v_mul_f32_e32 v101, 0xbfb8aa3b, v107
; __device__ __forceinline__ unsigned cvt_pk_bf16(float lo, float hi) { unsigned r; asm volatile("v_cvt_pk_bf16_f32 %0, %1, %2" : "=v"(r) : "v"(lo), "v"(hi)); return r; }
; __device__ __forceinline__ float silu_mul(float g, float u) { return g * u * __builtin_amdgcn_rcpf(1.0f + __builtin_amdgcn_exp2f(-1.4426950408889634f * g)); }
;     __device__ __forceinline__ void operator()(const f32x4 (&acc)[2][2][4][2], const Unit& u, int wr, int wc, int fr, int fq) const {
;     ...
;             for (int m = 0; m < 4; ++m) {
;                 const int row = row0 + ai * HALF + m * 16; const float rs = rsv[ai * 4 + m];
;                 const f32x4 g0 = acc[ai][0][m][0] * rs, g1 = acc[ai][0][m][1] * rs, u0 = acc[ai][1][m][0] * rs, u1 = acc[ai][1][m][1] * rs;
;                 u32x4e w;
;                 w.x = cvt_pk_bf16(silu_mul(g0[0], u0[0]), silu_mul(g0[1], u0[1])); w.y = cvt_pk_bf16(silu_mul(g0[2], u0[2]), silu_mul(g0[3], u0[3]));
;                 w.z = cvt_pk_bf16(silu_mul(g1[0], u1[0]), silu_mul(g1[1], u1[1])); w.w = cvt_pk_bf16(silu_mul(g1[2], u1[2]), silu_mul(g1[3], u1[3]));
;                 *(u32x4e*)(O + (size_t)row * ldo + col0) = w;
	v_exp_f32_e32 v101, v101
	v_mul_f32_e32 v98, v98, v100
	v_mul_f32_e32 v100, 0xbfb8aa3b, v105
	v_exp_f32_e32 v100, v100
	v_add_f32_e32 v101, 1.0, v101
	v_rcp_f32_e32 v101, v101
	v_add_f32_e32 v100, 1.0, v100
	v_rcp_f32_e32 v100, v100
	s_nop 0
	v_mul_f32_e32 v99, v99, v100
	v_mul_f32_e32 v100, 0xbfb8aa3b, v106
	v_exp_f32_e32 v100, v100
	v_cvt_pk_bf16_f32 v98, v98, v99
	v_mul_f32_e32 v99, v106, v118
	v_add_f32_e32 v100, 1.0, v100
	v_rcp_f32_e32 v100, v100
	s_nop 0
	v_mul_f32_e32 v99, v99, v100
	v_mul_f32_e32 v100, v107, v119
	v_mul_f32_e32 v100, v100, v101
	v_cvt_pk_bf16_f32 v99, v99, v100
	v_mad_i64_i32 v[100:101], s[10:11], v117, s24, v[112:113]
	v_lshl_add_u64 v[100:101], v[100:101], 0, v[114:115]
	global_store_dwordx4 v[100:101], v[96:99], off nt
	s_nop 1
	v_pk_mul_f32 v[96:97], v[82:83], v[142:143] op_sel_hi:[1,0]
	v_pk_mul_f32 v[82:83], v[80:81], v[142:143] op_sel_hi:[1,0]
	v_mul_f32_e32 v81, 0xbfb8aa3b, v92
	v_mul_f32_e32 v80, v92, v84
	v_exp_f32_e32 v81, v81
	v_mul_f32_e32 v84, 0xbfb8aa3b, v93
	v_exp_f32_e32 v84, v84
	v_mul_f32_e32 v82, v88, v82
	v_add_f32_e32 v81, 1.0, v81
	v_rcp_f32_e32 v81, v81
	v_add_f32_e32 v84, 1.0, v84
	v_rcp_f32_e32 v84, v84
	v_mul_f32_e32 v83, v89, v83
	v_mul_f32_e32 v80, v80, v81
	v_mul_f32_e32 v81, v93, v85
	v_mul_f32_e32 v81, v81, v84
	v_mul_f32_e32 v84, 0xbfb8aa3b, v94
	v_exp_f32_e32 v84, v84
	v_mul_f32_e32 v85, 0xbfb8aa3b, v95
	v_exp_f32_e32 v85, v85
	v_cvt_pk_bf16_f32 v80, v80, v81
	v_add_f32_e32 v84, 1.0, v84
	v_rcp_f32_e32 v84, v84
	v_add_f32_e32 v85, 1.0, v85
	v_rcp_f32_e32 v85, v85
	v_mul_f32_e32 v81, v94, v86
	v_mul_f32_e32 v81, v81, v84
	v_mul_f32_e32 v84, v95, v87
	v_mul_f32_e32 v84, v84, v85
	v_cvt_pk_bf16_f32 v81, v81, v84
	v_mul_f32_e32 v84, 0xbfb8aa3b, v88
	v_exp_f32_e32 v84, v84
	v_mul_f32_e32 v85, 0xbfb8aa3b, v91
	v_exp_f32_e32 v85, v85
	v_or_b32_e32 v98, 32, v153
	v_add_f32_e32 v84, 1.0, v84
	v_rcp_f32_e32 v84, v84
	v_add_f32_e32 v85, 1.0, v85
	v_rcp_f32_e32 v85, v85
	v_mul_f32_e32 v82, v82, v84
	v_mul_f32_e32 v84, 0xbfb8aa3b, v89
	v_exp_f32_e32 v84, v84
	s_nop 0
	v_add_f32_e32 v84, 1.0, v84
	v_rcp_f32_e32 v84, v84
	s_nop 0
	v_mul_f32_e32 v83, v83, v84
	v_mul_f32_e32 v84, 0xbfb8aa3b, v90
	v_exp_f32_e32 v84, v84
	v_cvt_pk_bf16_f32 v82, v82, v83
	v_mul_f32_e32 v83, v90, v96
	v_add_f32_e32 v84, 1.0, v84
	v_rcp_f32_e32 v84, v84
	s_nop 0
	v_mul_f32_e32 v83, v83, v84
	v_mul_f32_e32 v84, v91, v97
	v_mul_f32_e32 v84, v84, v85
	v_cvt_pk_bf16_f32 v83, v83, v84
	v_mad_i64_i32 v[84:85], s[10:11], v98, s24, v[112:113]
	v_lshl_add_u64 v[84:85], v[84:85], 0, v[114:115]
	global_store_dwordx4 v[84:85], v[80:83], off nt
	s_nop 1
	v_or_b32_e32 v81, 48, v153
	v_mov_b32_e32 v80, v143
	v_pk_mul_f32 v[76:77], v[76:77], v[80:81] op_sel_hi:[1,0]
	v_pk_mul_f32 v[68:69], v[68:69], v[80:81] op_sel_hi:[1,0]
	v_pk_mul_f32 v[82:83], v[66:67], v[80:81] op_sel_hi:[1,0]
	v_pk_mul_f32 v[66:67], v[64:65], v[80:81] op_sel_hi:[1,0]
	v_mul_f32_e32 v65, 0xbfb8aa3b, v76
	v_mul_f32_e32 v64, v76, v68
	v_exp_f32_e32 v65, v65
	v_mul_f32_e32 v68, 0xbfb8aa3b, v77
	v_exp_f32_e32 v68, v68
	v_pk_mul_f32 v[78:79], v[78:79], v[80:81] op_sel_hi:[1,0]
	v_add_f32_e32 v65, 1.0, v65
	v_rcp_f32_e32 v65, v65
	v_add_f32_e32 v68, 1.0, v68
	v_rcp_f32_e32 v68, v68
	v_pk_mul_f32 v[70:71], v[70:71], v[80:81] op_sel_hi:[1,0]
	v_mul_f32_e32 v64, v64, v65
	v_mul_f32_e32 v65, v77, v69
	v_mul_f32_e32 v65, v65, v68
	v_mul_f32_e32 v68, 0xbfb8aa3b, v78
	v_exp_f32_e32 v68, v68
	v_mul_f32_e32 v69, 0xbfb8aa3b, v79
	v_exp_f32_e32 v69, v69
	v_cvt_pk_bf16_f32 v64, v64, v65
	v_add_f32_e32 v68, 1.0, v68
	v_rcp_f32_e32 v68, v68
	v_add_f32_e32 v69, 1.0, v69
	v_rcp_f32_e32 v69, v69
	v_mul_f32_e32 v65, v78, v70
	v_mul_f32_e32 v65, v65, v68
	v_mul_f32_e32 v68, v79, v71
	v_pk_mul_f32 v[72:73], v[72:73], v[80:81] op_sel_hi:[1,0]
	v_mul_f32_e32 v68, v68, v69
	v_cvt_pk_bf16_f32 v65, v65, v68
	v_mul_f32_e32 v68, 0xbfb8aa3b, v72
	v_exp_f32_e32 v68, v68
	v_mul_f32_e32 v66, v72, v66
	v_pk_mul_f32 v[74:75], v[74:75], v[80:81] op_sel_hi:[1,0]
	v_mul_f32_e32 v67, v73, v67
	v_add_f32_e32 v68, 1.0, v68
	v_rcp_f32_e32 v68, v68
	v_mul_f32_e32 v69, 0xbfb8aa3b, v75
	v_exp_f32_e32 v69, v69
	v_mul_f32_e32 v66, v66, v68
	v_mul_f32_e32 v68, 0xbfb8aa3b, v73
	v_exp_f32_e32 v68, v68
	v_add_f32_e32 v69, 1.0, v69
	v_rcp_f32_e32 v69, v69
	v_add_f32_e32 v68, 1.0, v68
	v_rcp_f32_e32 v68, v68
	s_nop 0
	v_mul_f32_e32 v67, v67, v68
	v_mul_f32_e32 v68, 0xbfb8aa3b, v74
	v_exp_f32_e32 v68, v68
	v_cvt_pk_bf16_f32 v66, v66, v67
	v_mul_f32_e32 v67, v74, v82
	v_add_f32_e32 v68, 1.0, v68
	v_rcp_f32_e32 v68, v68
	s_nop 0
	v_mul_f32_e32 v67, v67, v68
	v_mul_f32_e32 v68, v75, v83
	v_mul_f32_e32 v68, v68, v69
	v_cvt_pk_bf16_f32 v67, v67, v68
	v_mad_i64_i32 v[68:69], s[10:11], v81, s24, v[112:113]
	v_lshl_add_u64 v[68:69], v[68:69], 0, v[114:115]
	global_store_dwordx4 v[68:69], v[64:67], off nt
	s_nop 1
	v_pk_mul_f32 v[64:65], v[50:51], v[140:141] op_sel_hi:[1,0]
	v_pk_mul_f32 v[50:51], v[48:49], v[140:141] op_sel_hi:[1,0]
	v_mul_f32_e32 v49, 0xbfb8aa3b, v60
	v_mul_f32_e32 v48, v60, v52
	v_exp_f32_e32 v49, v49
	v_mul_f32_e32 v52, 0xbfb8aa3b, v61
	v_exp_f32_e32 v52, v52
	v_mul_f32_e32 v50, v56, v50
	v_add_f32_e32 v49, 1.0, v49
	v_rcp_f32_e32 v49, v49
	v_add_f32_e32 v52, 1.0, v52
	v_rcp_f32_e32 v52, v52
	v_mul_f32_e32 v51, v57, v51
	v_mul_f32_e32 v48, v48, v49
	v_mul_f32_e32 v49, v61, v53
	v_mul_f32_e32 v49, v49, v52
	v_mul_f32_e32 v52, 0xbfb8aa3b, v62
	v_exp_f32_e32 v52, v52
	v_mul_f32_e32 v53, 0xbfb8aa3b, v63
	v_exp_f32_e32 v53, v53
	v_cvt_pk_bf16_f32 v48, v48, v49
	v_add_f32_e32 v52, 1.0, v52
	v_rcp_f32_e32 v52, v52
	v_add_f32_e32 v53, 1.0, v53
	v_rcp_f32_e32 v53, v53
	v_mul_f32_e32 v49, v62, v54
; __device__ __forceinline__ unsigned cvt_pk_bf16(float lo, float hi) { unsigned r; asm volatile("v_cvt_pk_bf16_f32 %0, %1, %2" : "=v"(r) : "v"(lo), "v"(hi)); return r; }
; __device__ __forceinline__ float silu_mul(float g, float u) { return g * u * __builtin_amdgcn_rcpf(1.0f + __builtin_amdgcn_exp2f(-1.4426950408889634f * g)); }
;     __device__ __forceinline__ void operator()(const f32x4 (&acc)[2][2][4][2], const Unit& u, int wr, int wc, int fr, int fq) const {
;     ...
;             for (int m = 0; m < 4; ++m) {
;                 const int row = row0 + ai * HALF + m * 16; const float rs = rsv[ai * 4 + m];
;                 const f32x4 g0 = acc[ai][0][m][0] * rs, g1 = acc[ai][0][m][1] * rs, u0 = acc[ai][1][m][0] * rs, u1 = acc[ai][1][m][1] * rs;
;                 u32x4e w;
;                 w.x = cvt_pk_bf16(silu_mul(g0[0], u0[0]), silu_mul(g0[1], u0[1])); w.y = cvt_pk_bf16(silu_mul(g0[2], u0[2]), silu_mul(g0[3], u0[3]));
;                 w.z = cvt_pk_bf16(silu_mul(g1[0], u1[0]), silu_mul(g1[1], u1[1])); w.w = cvt_pk_bf16(silu_mul(g1[2], u1[2]), silu_mul(g1[3], u1[3]));
;                 *(u32x4e*)(O + (size_t)row * ldo + col0) = w;
	v_mul_f32_e32 v49, v49, v52
	v_mul_f32_e32 v52, v63, v55
	v_mul_f32_e32 v52, v52, v53
	v_cvt_pk_bf16_f32 v49, v49, v52
	v_mul_f32_e32 v52, 0xbfb8aa3b, v56
	v_exp_f32_e32 v52, v52
	v_mul_f32_e32 v53, 0xbfb8aa3b, v59
	v_exp_f32_e32 v53, v53
	v_add_u32_e32 v66, 0x80, v153
	v_add_f32_e32 v52, 1.0, v52
	v_rcp_f32_e32 v52, v52
	v_add_f32_e32 v53, 1.0, v53
	v_rcp_f32_e32 v53, v53
	v_mul_f32_e32 v50, v50, v52
	v_mul_f32_e32 v52, 0xbfb8aa3b, v57
	v_exp_f32_e32 v52, v52
	s_nop 0
	v_add_f32_e32 v52, 1.0, v52
	v_rcp_f32_e32 v52, v52
	s_nop 0
	v_mul_f32_e32 v51, v51, v52
	v_mul_f32_e32 v52, 0xbfb8aa3b, v58
	v_exp_f32_e32 v52, v52
	v_cvt_pk_bf16_f32 v50, v50, v51
	v_mul_f32_e32 v51, v58, v64
	v_add_f32_e32 v52, 1.0, v52
	v_rcp_f32_e32 v52, v52
	s_nop 0
	v_mul_f32_e32 v51, v51, v52
	v_mul_f32_e32 v52, v59, v65
	v_mul_f32_e32 v52, v52, v53
	v_cvt_pk_bf16_f32 v51, v51, v52
	v_mad_i64_i32 v[52:53], s[10:11], v66, s24, v[112:113]
	v_lshl_add_u64 v[52:53], v[52:53], 0, v[114:115]
	global_store_dwordx4 v[52:53], v[48:51], off nt
	s_nop 1
	v_add_u32_e32 v49, 0x90, v153
	v_mov_b32_e32 v48, v141
	v_pk_mul_f32 v[44:45], v[44:45], v[48:49] op_sel_hi:[1,0]
	v_pk_mul_f32 v[36:37], v[36:37], v[48:49] op_sel_hi:[1,0]
	v_pk_mul_f32 v[50:51], v[34:35], v[48:49] op_sel_hi:[1,0]
	v_pk_mul_f32 v[34:35], v[32:33], v[48:49] op_sel_hi:[1,0]
	v_mul_f32_e32 v33, 0xbfb8aa3b, v44
	v_mul_f32_e32 v32, v44, v36
	v_exp_f32_e32 v33, v33
	v_mul_f32_e32 v36, 0xbfb8aa3b, v45
	v_exp_f32_e32 v36, v36
	v_pk_mul_f32 v[46:47], v[46:47], v[48:49] op_sel_hi:[1,0]
	v_add_f32_e32 v33, 1.0, v33
	v_rcp_f32_e32 v33, v33
	v_add_f32_e32 v36, 1.0, v36
	v_rcp_f32_e32 v36, v36
	v_pk_mul_f32 v[38:39], v[38:39], v[48:49] op_sel_hi:[1,0]
	v_mul_f32_e32 v32, v32, v33
	v_mul_f32_e32 v33, v45, v37
	v_mul_f32_e32 v33, v33, v36
	v_mul_f32_e32 v36, 0xbfb8aa3b, v46
	v_exp_f32_e32 v36, v36
	v_mul_f32_e32 v37, 0xbfb8aa3b, v47
	v_exp_f32_e32 v37, v37
	v_cvt_pk_bf16_f32 v32, v32, v33
	v_add_f32_e32 v36, 1.0, v36
	v_rcp_f32_e32 v36, v36
	v_add_f32_e32 v37, 1.0, v37
	v_rcp_f32_e32 v37, v37
	v_mul_f32_e32 v33, v46, v38
	v_mul_f32_e32 v33, v33, v36
	v_mul_f32_e32 v36, v47, v39
	v_pk_mul_f32 v[40:41], v[40:41], v[48:49] op_sel_hi:[1,0]
	v_mul_f32_e32 v36, v36, v37
	v_cvt_pk_bf16_f32 v33, v33, v36
	v_mul_f32_e32 v36, 0xbfb8aa3b, v40
	v_exp_f32_e32 v36, v36
	v_mul_f32_e32 v34, v40, v34
	v_pk_mul_f32 v[42:43], v[42:43], v[48:49] op_sel_hi:[1,0]
	v_mul_f32_e32 v35, v41, v35
	v_add_f32_e32 v36, 1.0, v36
	v_rcp_f32_e32 v36, v36
	v_mul_f32_e32 v37, 0xbfb8aa3b, v43
	v_exp_f32_e32 v37, v37
	v_mul_f32_e32 v34, v34, v36
	v_mul_f32_e32 v36, 0xbfb8aa3b, v41
	v_exp_f32_e32 v36, v36
	v_add_f32_e32 v37, 1.0, v37
	v_rcp_f32_e32 v37, v37
	v_add_f32_e32 v36, 1.0, v36
	v_rcp_f32_e32 v36, v36
	s_nop 0
	v_mul_f32_e32 v35, v35, v36
	v_mul_f32_e32 v36, 0xbfb8aa3b, v42
	v_exp_f32_e32 v36, v36
	v_cvt_pk_bf16_f32 v34, v34, v35
	v_mul_f32_e32 v35, v42, v50
	v_add_f32_e32 v36, 1.0, v36
	v_rcp_f32_e32 v36, v36
	s_nop 0
	v_mul_f32_e32 v35, v35, v36
	v_mul_f32_e32 v36, v43, v51
	v_mul_f32_e32 v36, v36, v37
	v_cvt_pk_bf16_f32 v35, v35, v36
	v_mad_i64_i32 v[36:37], s[10:11], v49, s24, v[112:113]
	v_lshl_add_u64 v[36:37], v[36:37], 0, v[114:115]
	global_store_dwordx4 v[36:37], v[32:35], off nt
	s_nop 1
	v_pk_mul_f32 v[32:33], v[18:19], v[138:139] op_sel_hi:[1,0]
	v_pk_mul_f32 v[18:19], v[16:17], v[138:139] op_sel_hi:[1,0]
	v_mul_f32_e32 v17, 0xbfb8aa3b, v28
	v_mul_f32_e32 v16, v28, v20
	v_exp_f32_e32 v17, v17
	v_mul_f32_e32 v20, 0xbfb8aa3b, v29
	v_exp_f32_e32 v20, v20
	v_mul_f32_e32 v18, v24, v18
	v_add_f32_e32 v17, 1.0, v17
	v_rcp_f32_e32 v17, v17
	v_add_f32_e32 v20, 1.0, v20
	v_rcp_f32_e32 v20, v20
; __device__ __forceinline__ unsigned cvt_pk_bf16(float lo, float hi) { unsigned r; asm volatile("v_cvt_pk_bf16_f32 %0, %1, %2" : "=v"(r) : "v"(lo), "v"(hi)); return r; }
; __device__ __forceinline__ float silu_mul(float g, float u) { return g * u * __builtin_amdgcn_rcpf(1.0f + __builtin_amdgcn_exp2f(-1.4426950408889634f * g)); }
;     __device__ __forceinline__ void operator()(const f32x4 (&acc)[2][2][4][2], const Unit& u, int wr, int wc, int fr, int fq) const {
;     ...
;             for (int m = 0; m < 4; ++m) {
;                 const int row = row0 + ai * HALF + m * 16; const float rs = rsv[ai * 4 + m];
;                 const f32x4 g0 = acc[ai][0][m][0] * rs, g1 = acc[ai][0][m][1] * rs, u0 = acc[ai][1][m][0] * rs, u1 = acc[ai][1][m][1] * rs;
;                 u32x4e w;
;                 w.x = cvt_pk_bf16(silu_mul(g0[0], u0[0]), silu_mul(g0[1], u0[1])); w.y = cvt_pk_bf16(silu_mul(g0[2], u0[2]), silu_mul(g0[3], u0[3]));
;                 w.z = cvt_pk_bf16(silu_mul(g1[0], u1[0]), silu_mul(g1[1], u1[1])); w.w = cvt_pk_bf16(silu_mul(g1[2], u1[2]), silu_mul(g1[3], u1[3]));
;                 *(u32x4e*)(O + (size_t)row * ldo + col0) = w;
;             }
	v_mul_f32_e32 v19, v25, v19
	v_mul_f32_e32 v16, v16, v17
	v_mul_f32_e32 v17, v29, v21
	v_mul_f32_e32 v17, v17, v20
	v_mul_f32_e32 v20, 0xbfb8aa3b, v30
	v_exp_f32_e32 v20, v20
	v_mul_f32_e32 v21, 0xbfb8aa3b, v31
	v_exp_f32_e32 v21, v21
	v_cvt_pk_bf16_f32 v16, v16, v17
	v_add_f32_e32 v20, 1.0, v20
	v_rcp_f32_e32 v20, v20
	v_add_f32_e32 v21, 1.0, v21
	v_rcp_f32_e32 v21, v21
	v_mul_f32_e32 v17, v30, v22
	v_mul_f32_e32 v17, v17, v20
	v_mul_f32_e32 v20, v31, v23
	v_mul_f32_e32 v20, v20, v21
	v_cvt_pk_bf16_f32 v17, v17, v20
	v_mul_f32_e32 v20, 0xbfb8aa3b, v24
	v_exp_f32_e32 v20, v20
	v_mul_f32_e32 v21, 0xbfb8aa3b, v27
	v_exp_f32_e32 v21, v21
	v_add_u32_e32 v34, 0xa0, v153
	v_add_f32_e32 v20, 1.0, v20
	v_rcp_f32_e32 v20, v20
	v_add_f32_e32 v21, 1.0, v21
	v_rcp_f32_e32 v21, v21
	v_mul_f32_e32 v18, v18, v20
	v_mul_f32_e32 v20, 0xbfb8aa3b, v25
	v_exp_f32_e32 v20, v20
	s_nop 0
	v_add_f32_e32 v20, 1.0, v20
	v_rcp_f32_e32 v20, v20
	s_nop 0
	v_mul_f32_e32 v19, v19, v20
	v_mul_f32_e32 v20, 0xbfb8aa3b, v26
	v_exp_f32_e32 v20, v20
	v_cvt_pk_bf16_f32 v18, v18, v19
	v_mul_f32_e32 v19, v26, v32
	v_add_f32_e32 v20, 1.0, v20
	v_rcp_f32_e32 v20, v20
	s_nop 0
	v_mul_f32_e32 v19, v19, v20
	v_mul_f32_e32 v20, v27, v33
	v_mul_f32_e32 v20, v20, v21
	v_cvt_pk_bf16_f32 v19, v19, v20
	v_mad_i64_i32 v[20:21], s[10:11], v34, s24, v[112:113]
	v_lshl_add_u64 v[20:21], v[20:21], 0, v[114:115]
	global_store_dwordx4 v[20:21], v[16:19], off nt
	s_nop 1
	v_add_u32_e32 v17, 0xb0, v153
	v_mov_b32_e32 v16, v139
	v_pk_mul_f32 v[12:13], v[12:13], v[16:17] op_sel_hi:[1,0]
	v_pk_mul_f32 v[4:5], v[4:5], v[16:17] op_sel_hi:[1,0]
	v_pk_mul_f32 v[18:19], v[2:3], v[16:17] op_sel_hi:[1,0]
	v_pk_mul_f32 v[2:3], v[0:1], v[16:17] op_sel_hi:[1,0]
	v_mul_f32_e32 v1, 0xbfb8aa3b, v12
	v_mul_f32_e32 v0, v12, v4
	v_exp_f32_e32 v1, v1
	v_mul_f32_e32 v4, 0xbfb8aa3b, v13
	v_exp_f32_e32 v4, v4
	v_pk_mul_f32 v[14:15], v[14:15], v[16:17] op_sel_hi:[1,0]
	v_add_f32_e32 v1, 1.0, v1
	v_rcp_f32_e32 v1, v1
	v_add_f32_e32 v4, 1.0, v4
	v_rcp_f32_e32 v4, v4
	v_pk_mul_f32 v[6:7], v[6:7], v[16:17] op_sel_hi:[1,0]
	v_mul_f32_e32 v0, v0, v1
	v_mul_f32_e32 v1, v13, v5
	v_mul_f32_e32 v1, v1, v4
	v_mul_f32_e32 v4, 0xbfb8aa3b, v14
	v_exp_f32_e32 v4, v4
	v_mul_f32_e32 v5, 0xbfb8aa3b, v15
	v_exp_f32_e32 v5, v5
	v_cvt_pk_bf16_f32 v0, v0, v1
	v_add_f32_e32 v4, 1.0, v4
	v_rcp_f32_e32 v4, v4
	v_add_f32_e32 v5, 1.0, v5
	v_rcp_f32_e32 v5, v5
	v_mul_f32_e32 v1, v14, v6
	v_mul_f32_e32 v1, v1, v4
	v_mul_f32_e32 v4, v15, v7
	v_pk_mul_f32 v[8:9], v[8:9], v[16:17] op_sel_hi:[1,0]
	v_mul_f32_e32 v4, v4, v5
	v_cvt_pk_bf16_f32 v1, v1, v4
	v_mul_f32_e32 v4, 0xbfb8aa3b, v8
	v_exp_f32_e32 v4, v4
	v_mul_f32_e32 v2, v8, v2
	v_pk_mul_f32 v[10:11], v[10:11], v[16:17] op_sel_hi:[1,0]
	v_mul_f32_e32 v3, v9, v3
	v_add_f32_e32 v4, 1.0, v4
	v_rcp_f32_e32 v4, v4
	v_mul_f32_e32 v5, 0xbfb8aa3b, v11
	v_exp_f32_e32 v5, v5
	v_mul_f32_e32 v2, v2, v4
	v_mul_f32_e32 v4, 0xbfb8aa3b, v9
	v_exp_f32_e32 v4, v4
	v_add_f32_e32 v5, 1.0, v5
	v_rcp_f32_e32 v5, v5
	v_add_f32_e32 v4, 1.0, v4
	v_rcp_f32_e32 v4, v4
	s_nop 0
	v_mul_f32_e32 v3, v3, v4
	v_mul_f32_e32 v4, 0xbfb8aa3b, v10
	v_exp_f32_e32 v4, v4
	v_cvt_pk_bf16_f32 v2, v2, v3
	v_mul_f32_e32 v3, v10, v18
	v_add_f32_e32 v4, 1.0, v4
	v_rcp_f32_e32 v4, v4
	s_nop 0
	v_mul_f32_e32 v3, v3, v4
	v_mul_f32_e32 v4, v11, v19
	v_mul_f32_e32 v4, v4, v5
	v_cvt_pk_bf16_f32 v3, v3, v4
	v_mad_i64_i32 v[4:5], s[10:11], v17, s24, v[112:113]
	v_lshl_add_u64 v[4:5], v[4:5], 0, v[114:115]
	s_mov_b64 s[10:11], -1
	global_store_dwordx4 v[4:5], v[0:3], off nt
	s_cbranch_vccnz .LBB0_395
	s_andn2_b64 vcc, exec, s[4:5]
	s_cbranch_vccnz .LBB0_394
	s_barrier
	s_branch .LBB0_394
